# x4 main loops + x3/trim remaining loops + xgen + prologue x-loop with 8 loads in flight and DPP row sums
# speedup vs baseline: 1.0133x; 1.0133x over previous
; __device__ __forceinline__ unsigned cvt_pk_bf16(float lo, float hi) { const f32x2_t v = {lo, hi}; const bf16x2_t r = __builtin_convertvector(v, bf16x2_t); return __builtin_bit_cast(unsigned, r); }
; __device__ __forceinline__ float wave_sum(float v) {
; #pragma unroll
;     for (int o = 1; o < 64; o <<= 1) v += __shfl_xor(v, o);
;     return v;
; }
; __device__ __forceinline__ void p_prologue(Frame& F, int stage, int part, int nparts) {
;     ...
;         for (int m = gw; m < MROWS; m += NGW) {
;             const f32x4* xr = (const f32x4*)(x + (size_t)m * DM) + lane; u32x2* br = (u32x2*)(HB + (size_t)m * DM) + lane;
; #pragma unroll
;             for (int j = 0; j < 8; ++j) { const f32x4 v = xr[64 * j]; u32x2 w; w.x = cvt_pk_bf16(v[0], v[1]); w.y = cvt_pk_bf16(v[2], v[3]); br[64 * j] = w;
;                 const float s = wave_sum((v[0] * v[0] + v[1] * v[1]) + (v[2] * v[2] + v[3] * v[3])); if (lane == 0) SS[(size_t)j * MROWS + m] = s; }
.LBB0_15:
	s_waitcnt lgkmcnt(0)
	global_load_dwordx4 v[32:35], v[4:5], off offset:-4096
	global_load_dwordx4 v[36:39], v[4:5], off offset:-3072
	global_load_dwordx4 v[40:43], v[4:5], off offset:-2048
	global_load_dwordx4 v[44:47], v[4:5], off offset:-1024
	global_load_dwordx4 v[48:51], v[4:5], off
	global_load_dwordx4 v[52:55], v[4:5], off offset:1024
	global_load_dwordx4 v[56:59], v[4:5], off offset:2048
	global_load_dwordx4 v[60:63], v[4:5], off offset:3072
	s_add_u32 s26, s54, s18
	s_addc_u32 s27, s55, s19
	v_lshl_add_u64 v[8:9], s[54:55], 0, v[6:7]
	v_add_co_u32_e32 v26, vcc, s5, v8
	s_nop 1
	v_addc_co_u32_e32 v27, vcc, 0, v9, vcc
	s_mov_b64 s[28:29], exec
	s_waitcnt vmcnt(7)
	v_mul_f32_e32 v28, v33, v33
	v_mul_f32_e32 v29, v35, v35
	v_fmac_f32_e32 v28, v32, v32
	v_fmac_f32_e32 v29, v34, v34
	v_cvt_pk_bf16_f32 v30, v32, v33
	v_add_f32_e32 v28, v28, v29
	v_cvt_pk_bf16_f32 v31, v34, v35
	s_nop 0
	v_add_f32_dpp v28, v28, v28 quad_perm:[1,0,3,2] row_mask:0xf bank_mask:0xf
	s_nop 1
	v_add_f32_dpp v28, v28, v28 quad_perm:[2,3,0,1] row_mask:0xf bank_mask:0xf
	s_nop 1
	v_add_f32_dpp v28, v28, v28 row_half_mirror row_mask:0xf bank_mask:0xf
	s_nop 1
	v_add_f32_dpp v28, v28, v28 row_mirror row_mask:0xf bank_mask:0xf
	s_nop 1
	v_add_f32_dpp v28, v28, v28 row_bcast:15 row_mask:0xa bank_mask:0xf
	s_nop 1
	v_add_f32_dpp v28, v28, v28 row_bcast:31 row_mask:0xc bank_mask:0xf
	global_store_dwordx2 v[26:27], v[30:31], off
	s_nop 0
	v_readlane_b32 s100, v28, 63
	s_nop 3
	v_mov_b32_e32 v29, s100
	s_mov_b64 exec, s[0:1]
	global_store_dword v3, v29, s[26:27]
	s_mov_b64 exec, s[28:29]
	s_waitcnt vmcnt(8)
	v_mul_f32_e32 v28, v37, v37
	v_mul_f32_e32 v29, v39, v39
	v_fmac_f32_e32 v28, v36, v36
	v_fmac_f32_e32 v29, v38, v38
	v_cvt_pk_bf16_f32 v30, v36, v37
	v_add_f32_e32 v28, v28, v29
	v_cvt_pk_bf16_f32 v31, v38, v39
	s_nop 0
	v_add_f32_dpp v28, v28, v28 quad_perm:[1,0,3,2] row_mask:0xf bank_mask:0xf
	s_nop 1
	v_add_f32_dpp v28, v28, v28 quad_perm:[2,3,0,1] row_mask:0xf bank_mask:0xf
	s_nop 1
	v_add_f32_dpp v28, v28, v28 row_half_mirror row_mask:0xf bank_mask:0xf
	s_nop 1
	v_add_f32_dpp v28, v28, v28 row_mirror row_mask:0xf bank_mask:0xf
	s_nop 1
	v_add_f32_dpp v28, v28, v28 row_bcast:15 row_mask:0xa bank_mask:0xf
	s_nop 1
	v_add_f32_dpp v28, v28, v28 row_bcast:31 row_mask:0xc bank_mask:0xf
	global_store_dwordx2 v[26:27], v[30:31], off offset:512
	s_nop 0
	v_readlane_b32 s100, v28, 63
	s_nop 3
	v_mov_b32_e32 v29, s100
	s_mov_b64 exec, s[0:1]
	global_store_dword v17, v29, s[26:27]
	s_mov_b64 exec, s[28:29]
	s_waitcnt vmcnt(9)
	v_mul_f32_e32 v28, v41, v41
	v_mul_f32_e32 v29, v43, v43
	v_fmac_f32_e32 v28, v40, v40
	v_fmac_f32_e32 v29, v42, v42
	v_cvt_pk_bf16_f32 v30, v40, v41
	v_add_f32_e32 v28, v28, v29
	v_cvt_pk_bf16_f32 v31, v42, v43
	s_nop 0
	v_add_f32_dpp v28, v28, v28 quad_perm:[1,0,3,2] row_mask:0xf bank_mask:0xf
	s_nop 1
	v_add_f32_dpp v28, v28, v28 quad_perm:[2,3,0,1] row_mask:0xf bank_mask:0xf
	s_nop 1
	v_add_f32_dpp v28, v28, v28 row_half_mirror row_mask:0xf bank_mask:0xf
	s_nop 1
	v_add_f32_dpp v28, v28, v28 row_mirror row_mask:0xf bank_mask:0xf
	s_nop 1
	v_add_f32_dpp v28, v28, v28 row_bcast:15 row_mask:0xa bank_mask:0xf
	s_nop 1
	v_add_f32_dpp v28, v28, v28 row_bcast:31 row_mask:0xc bank_mask:0xf
	global_store_dwordx2 v[26:27], v[30:31], off offset:1024
	s_nop 0
	v_readlane_b32 s100, v28, 63
	s_nop 3
	v_mov_b32_e32 v29, s100
	s_mov_b64 exec, s[0:1]
	global_store_dword v18, v29, s[26:27]
	s_mov_b64 exec, s[28:29]
	s_waitcnt vmcnt(10)
	v_mul_f32_e32 v28, v45, v45
	v_mul_f32_e32 v29, v47, v47
	v_fmac_f32_e32 v28, v44, v44
	v_fmac_f32_e32 v29, v46, v46
	v_cvt_pk_bf16_f32 v30, v44, v45
	v_add_f32_e32 v28, v28, v29
	v_cvt_pk_bf16_f32 v31, v46, v47
	s_nop 0
	v_add_f32_dpp v28, v28, v28 quad_perm:[1,0,3,2] row_mask:0xf bank_mask:0xf
	s_nop 1
	v_add_f32_dpp v28, v28, v28 quad_perm:[2,3,0,1] row_mask:0xf bank_mask:0xf
	s_nop 1
	v_add_f32_dpp v28, v28, v28 row_half_mirror row_mask:0xf bank_mask:0xf
	s_nop 1
	v_add_f32_dpp v28, v28, v28 row_mirror row_mask:0xf bank_mask:0xf
	s_nop 1
	v_add_f32_dpp v28, v28, v28 row_bcast:15 row_mask:0xa bank_mask:0xf
	s_nop 1
	v_add_f32_dpp v28, v28, v28 row_bcast:31 row_mask:0xc bank_mask:0xf
	global_store_dwordx2 v[26:27], v[30:31], off offset:1536
	s_nop 0
	v_readlane_b32 s100, v28, 63
	s_nop 3
	v_mov_b32_e32 v29, s100
	s_mov_b64 exec, s[0:1]
	global_store_dword v19, v29, s[26:27]
	s_mov_b64 exec, s[28:29]
	s_waitcnt vmcnt(11)
; __device__ __forceinline__ unsigned cvt_pk_bf16(float lo, float hi) { const f32x2_t v = {lo, hi}; const bf16x2_t r = __builtin_convertvector(v, bf16x2_t); return __builtin_bit_cast(unsigned, r); }
; __device__ __forceinline__ float wave_sum(float v) {
; #pragma unroll
;     for (int o = 1; o < 64; o <<= 1) v += __shfl_xor(v, o);
;     return v;
; }
; __device__ __forceinline__ void p_prologue(Frame& F, int stage, int part, int nparts) {
;     ...
;         for (int m = gw; m < MROWS; m += NGW) {
;             const f32x4* xr = (const f32x4*)(x + (size_t)m * DM) + lane; u32x2* br = (u32x2*)(HB + (size_t)m * DM) + lane;
; #pragma unroll
;             for (int j = 0; j < 8; ++j) { const f32x4 v = xr[64 * j]; u32x2 w; w.x = cvt_pk_bf16(v[0], v[1]); w.y = cvt_pk_bf16(v[2], v[3]); br[64 * j] = w;
;                 const float s = wave_sum((v[0] * v[0] + v[1] * v[1]) + (v[2] * v[2] + v[3] * v[3])); if (lane == 0) SS[(size_t)j * MROWS + m] = s; }
	v_mul_f32_e32 v28, v49, v49
	v_mul_f32_e32 v29, v51, v51
	v_fmac_f32_e32 v28, v48, v48
	v_fmac_f32_e32 v29, v50, v50
	v_cvt_pk_bf16_f32 v30, v48, v49
	v_add_f32_e32 v28, v28, v29
	v_cvt_pk_bf16_f32 v31, v50, v51
	s_nop 0
	v_add_f32_dpp v28, v28, v28 quad_perm:[1,0,3,2] row_mask:0xf bank_mask:0xf
	s_nop 1
	v_add_f32_dpp v28, v28, v28 quad_perm:[2,3,0,1] row_mask:0xf bank_mask:0xf
	s_nop 1
	v_add_f32_dpp v28, v28, v28 row_half_mirror row_mask:0xf bank_mask:0xf
	s_nop 1
	v_add_f32_dpp v28, v28, v28 row_mirror row_mask:0xf bank_mask:0xf
	s_nop 1
	v_add_f32_dpp v28, v28, v28 row_bcast:15 row_mask:0xa bank_mask:0xf
	s_nop 1
	v_add_f32_dpp v28, v28, v28 row_bcast:31 row_mask:0xc bank_mask:0xf
	global_store_dwordx2 v[26:27], v[30:31], off offset:2048
	s_nop 0
	v_readlane_b32 s100, v28, 63
	s_nop 3
	v_mov_b32_e32 v29, s100
	s_mov_b64 exec, s[0:1]
	global_store_dword v20, v29, s[26:27]
	s_mov_b64 exec, s[28:29]
	s_waitcnt vmcnt(12)
	v_mul_f32_e32 v28, v53, v53
	v_mul_f32_e32 v29, v55, v55
	v_fmac_f32_e32 v28, v52, v52
	v_fmac_f32_e32 v29, v54, v54
	v_cvt_pk_bf16_f32 v30, v52, v53
	v_add_f32_e32 v28, v28, v29
	v_cvt_pk_bf16_f32 v31, v54, v55
	s_nop 0
	v_add_f32_dpp v28, v28, v28 quad_perm:[1,0,3,2] row_mask:0xf bank_mask:0xf
	s_nop 1
	v_add_f32_dpp v28, v28, v28 quad_perm:[2,3,0,1] row_mask:0xf bank_mask:0xf
	s_nop 1
	v_add_f32_dpp v28, v28, v28 row_half_mirror row_mask:0xf bank_mask:0xf
	s_nop 1
	v_add_f32_dpp v28, v28, v28 row_mirror row_mask:0xf bank_mask:0xf
	s_nop 1
	v_add_f32_dpp v28, v28, v28 row_bcast:15 row_mask:0xa bank_mask:0xf
	s_nop 1
	v_add_f32_dpp v28, v28, v28 row_bcast:31 row_mask:0xc bank_mask:0xf
	global_store_dwordx2 v[26:27], v[30:31], off offset:2560
	s_nop 0
	v_readlane_b32 s100, v28, 63
	s_nop 3
	v_mov_b32_e32 v29, s100
	s_mov_b64 exec, s[0:1]
	global_store_dword v21, v29, s[26:27]
	s_mov_b64 exec, s[28:29]
	s_waitcnt vmcnt(13)
	v_mul_f32_e32 v28, v57, v57
	v_mul_f32_e32 v29, v59, v59
	v_fmac_f32_e32 v28, v56, v56
	v_fmac_f32_e32 v29, v58, v58
	v_cvt_pk_bf16_f32 v30, v56, v57
	v_add_f32_e32 v28, v28, v29
	v_cvt_pk_bf16_f32 v31, v58, v59
	s_nop 0
	v_add_f32_dpp v28, v28, v28 quad_perm:[1,0,3,2] row_mask:0xf bank_mask:0xf
	s_nop 1
	v_add_f32_dpp v28, v28, v28 quad_perm:[2,3,0,1] row_mask:0xf bank_mask:0xf
	s_nop 1
	v_add_f32_dpp v28, v28, v28 row_half_mirror row_mask:0xf bank_mask:0xf
	s_nop 1
	v_add_f32_dpp v28, v28, v28 row_mirror row_mask:0xf bank_mask:0xf
	s_nop 1
	v_add_f32_dpp v28, v28, v28 row_bcast:15 row_mask:0xa bank_mask:0xf
	s_nop 1
	v_add_f32_dpp v28, v28, v28 row_bcast:31 row_mask:0xc bank_mask:0xf
	global_store_dwordx2 v[26:27], v[30:31], off offset:3072
	s_nop 0
	v_readlane_b32 s100, v28, 63
	s_nop 3
	v_mov_b32_e32 v29, s100
	s_mov_b64 exec, s[0:1]
	global_store_dword v22, v29, s[26:27]
	s_mov_b64 exec, s[28:29]
	s_waitcnt vmcnt(14)
	v_mul_f32_e32 v28, v61, v61
	v_mul_f32_e32 v29, v63, v63
	v_fmac_f32_e32 v28, v60, v60
	v_fmac_f32_e32 v29, v62, v62
	v_cvt_pk_bf16_f32 v30, v60, v61
	v_add_f32_e32 v28, v28, v29
	v_cvt_pk_bf16_f32 v31, v62, v63
	s_nop 0
	v_add_f32_dpp v28, v28, v28 quad_perm:[1,0,3,2] row_mask:0xf bank_mask:0xf
	s_nop 1
	v_add_f32_dpp v28, v28, v28 quad_perm:[2,3,0,1] row_mask:0xf bank_mask:0xf
	s_nop 1
	v_add_f32_dpp v28, v28, v28 row_half_mirror row_mask:0xf bank_mask:0xf
	s_nop 1
	v_add_f32_dpp v28, v28, v28 row_mirror row_mask:0xf bank_mask:0xf
	s_nop 1
	v_add_f32_dpp v28, v28, v28 row_bcast:15 row_mask:0xa bank_mask:0xf
	s_nop 1
	v_add_f32_dpp v28, v28, v28 row_bcast:31 row_mask:0xc bank_mask:0xf
	global_store_dwordx2 v[26:27], v[30:31], off offset:3584
	s_nop 0
	v_readlane_b32 s100, v28, 63
	s_nop 3
	v_mov_b32_e32 v29, s100
	s_mov_b64 exec, s[0:1]
	global_store_dword v23, v29, s[26:27]
	s_mov_b64 exec, s[28:29]
	s_branch .LBB0_14
